# even in-proj: second-round super-tile column block flipped so every workgroup gets at most one transposed-V tile (slow epilogue) instead of two
# baseline (speedup 1.0000x reference)
;     ...
;   const bool xmap = (skip == 0) && ((nnt & 7) == 0) && ((nb & 63) == 0);
;   const int q = xmap ? (b & 7) * (nb >> 3) + (b >> 3) : b;
;   for (int t0 = 0; t0 < ntiles; t0 += nb) {
;     const int t = t0 + q;
;     if (t >= ntiles) break;
;     if (t < nmain) {
;       int mt, nt;
;       if (xmap) {
;         const int s_ = t >> 6, w_ = t & 63, spr = nnt >> 3;
;         const int sm = s_ / spr, sn = s_ - sm * spr;
;         mt = sm * 8 + (w_ >> 3);
;         nt = sn * 8 + (w_ & 7);
.LBB0_418:
	s_andn2_b64 vcc, exec, s[0:1]
	s_cbranch_vccnz .LBB0_420
	s_ashr_i32 s0, s13, 6
	s_lshr_b32 s1, s13, 31
	s_add_i32 s1, s0, s1
	s_ashr_i32 s1, s1, 1
	s_lshl_b32 s16, s1, 3
	s_lshl_b32 s1, s1, 4
	s_lshl_b32 s0, s0, 3
	s_bfe_u32 s17, s13, 0x30003
	s_sub_i32 s0, s0, s1
	s_and_b32 s1, s13, 7
	s_or_b32 s17, s16, s17
	s_or_b32 s16, s0, s1
	s_lshr_b32 s0, s13, 6
	s_and_b32 s0, s0, 8
	s_xor_b32 s16, s16, s0
